# m2b + hand-scheduled packed SwiGLU gate/up epilogue (P1/P6) + software-pipelined final RMSNorm loop
# speedup vs baseline: 1.0139x; 1.0139x over previous
; __device__ __forceinline__ unsigned pk4_fp8(float a, float b, float c, float d) { int w = 0; w = __builtin_amdgcn_cvt_pk_fp8_f32(clamp8(a), clamp8(b), w, false); w = __builtin_amdgcn_cvt_pk_fp8_f32(clamp8(c), clamp8(d), w, true); return (unsigned)w; }
; __device__ __forceinline__ float silu_mul(float g, float u) { return g * __builtin_amdgcn_rcpf(1.0f + __builtin_amdgcn_exp2f(-g * LOG2E)) * u; }
;     __device__ __forceinline__ void operator()(const f32x4 (&acc)[2][2][4][2], const Unit& u, int wr, int wc, int fr, int fq, const unsigned long long (&pf)[8]) const {
;         const int row0 = u.pm * BM + wr * 64 + fr, col0 = u.pn * HALF + wc * 32 + 8 * fq;
; #pragma unroll
;         for (int ai = 0; ai < 2; ++ai)
; #pragma unroll
;             for (int m = 0; m < 4; ++m) { const int row = row0 + ai * HALF + m * 16; const float rs = rsqrtf((float)pf[ai * 4 + m] * (1.0f / (SSQ_SCALE * 1024.0f)) + EPS) * wsc;
;                 const f32x4 g0 = acc[ai][0][m][0] * rs, g1 = acc[ai][0][m][1] * rs, u0 = acc[ai][1][m][0] * rs, u1 = acc[ai][1][m][1] * rs;
;                 u32x2 w; w.x = pk4_fp8(silu_mul(g0[0], u0[0]) * HFF8_SCALE, silu_mul(g0[1], u0[1]) * HFF8_SCALE, silu_mul(g0[2], u0[2]) * HFF8_SCALE, silu_mul(g0[3], u0[3]) * HFF8_SCALE);
;                 w.y = pk4_fp8(silu_mul(g1[0], u1[0]) * HFF8_SCALE, silu_mul(g1[1], u1[1]) * HFF8_SCALE, silu_mul(g1[2], u1[2]) * HFF8_SCALE, silu_mul(g1[3], u1[3]) * HFF8_SCALE);
;                 *(u32x2*)(O + (size_t)row * FF + col0) = w; }
.LBB0_246:
	s_nop 15
	s_nop 7
	s_waitcnt vmcnt(0)
	v_lshl_or_b32 v0, s33, 7, v220
	v_mov_b32_e32 v4, 0x358637bd
	v_ashrrev_i32_e32 v1, 31, v0
	v_mov_b64_e32 v[2:3], s[48:49]
	v_mov_b32_e32 v6, 1.0
	v_mov_b32_e32 v7, 1.0
	v_ffbh_u32_e32 v8, v183
	v_ffbh_u32_e32 v12, v181
	v_min_u32_e32 v10, 32, v8
	v_min_u32_e32 v14, 32, v12
	v_lshlrev_b64 v[8:9], v10, v[182:183]
	v_lshlrev_b64 v[12:13], v14, v[180:181]
	v_min_u32_e32 v8, 1, v8
	v_min_u32_e32 v12, 1, v12
	v_or_b32_e32 v8, v9, v8
	v_or_b32_e32 v12, v13, v12
	v_cvt_f32_u32_e32 v8, v8
	v_cvt_f32_u32_e32 v12, v12
	v_sub_u32_e32 v9, 32, v10
	v_sub_u32_e32 v13, 32, v14
	v_ldexp_f32 v8, v8, v9
	v_ldexp_f32 v12, v12, v13
	v_fma_f32 v8, v8, s80, v4
	v_fma_f32 v12, v12, s80, v4
	v_mul_f32_e32 v9, 0x4b800000, v8
	v_mul_f32_e32 v13, 0x4b800000, v12
	v_cmp_gt_f32_e32 vcc, s92, v8
	v_cmp_gt_f32_e64 s[12:13], s92, v12
	s_nop 0
	v_cndmask_b32_e32 v8, v8, v9, vcc
	v_cndmask_b32_e64 v12, v12, v13, s[12:13]
	v_rsq_f32_e32 v8, v8
	v_rsq_f32_e32 v12, v12
	v_mul_f32_e32 v9, 0x45800000, v8
	v_mul_f32_e32 v13, 0x45800000, v12
	v_cndmask_b32_e32 v8, v8, v9, vcc
	v_cndmask_b32_e64 v12, v12, v13, s[12:13]
	v_mul_f32_e32 v8, 0x3c800000, v8
	v_mul_f32_e32 v12, 0x3c800000, v12
	v_mul_f32_e32 v194, 0xbfb8aa3b, v8
	v_mul_f32_e32 v196, 0xbfb8aa3b, v12
	v_mul_f32_e32 v9, v8, v8
	v_mul_f32_e32 v13, v12, v12
	v_mul_f32_e32 v195, 0x41000000, v9
	v_mul_f32_e32 v197, 0x41000000, v13
	v_ffbh_u32_e32 v8, v185
	v_ffbh_u32_e32 v12, v179
	v_min_u32_e32 v10, 32, v8
	v_min_u32_e32 v14, 32, v12
	v_lshlrev_b64 v[8:9], v10, v[184:185]
	v_lshlrev_b64 v[12:13], v14, v[178:179]
	v_min_u32_e32 v8, 1, v8
	v_min_u32_e32 v12, 1, v12
	v_or_b32_e32 v8, v9, v8
	v_or_b32_e32 v12, v13, v12
	v_cvt_f32_u32_e32 v8, v8
	v_cvt_f32_u32_e32 v12, v12
	v_sub_u32_e32 v9, 32, v10
	v_sub_u32_e32 v13, 32, v14
	v_ldexp_f32 v8, v8, v9
	v_ldexp_f32 v12, v12, v13
	v_fma_f32 v8, v8, s80, v4
	v_fma_f32 v12, v12, s80, v4
	v_mul_f32_e32 v9, 0x4b800000, v8
	v_mul_f32_e32 v13, 0x4b800000, v12
	v_cmp_gt_f32_e32 vcc, s92, v8
	v_cmp_gt_f32_e64 s[12:13], s92, v12
	s_nop 0
	v_cndmask_b32_e32 v8, v8, v9, vcc
	v_cndmask_b32_e64 v12, v12, v13, s[12:13]
	v_rsq_f32_e32 v8, v8
	v_rsq_f32_e32 v12, v12
	v_mul_f32_e32 v9, 0x45800000, v8
	v_mul_f32_e32 v13, 0x45800000, v12
	v_cndmask_b32_e32 v8, v8, v9, vcc
	v_cndmask_b32_e64 v12, v12, v13, s[12:13]
	v_mul_f32_e32 v8, 0x3c800000, v8
	v_mul_f32_e32 v12, 0x3c800000, v12
	v_mul_f32_e32 v198, 0xbfb8aa3b, v8
	v_mul_f32_e32 v200, 0xbfb8aa3b, v12
	v_mul_f32_e32 v9, v8, v8
	v_mul_f32_e32 v13, v12, v12
	v_mul_f32_e32 v199, 0x41000000, v9
	v_mul_f32_e32 v201, 0x41000000, v13
	v_ffbh_u32_e32 v8, v187
	v_ffbh_u32_e32 v12, v177
	v_min_u32_e32 v10, 32, v8
	v_min_u32_e32 v14, 32, v12
	v_lshlrev_b64 v[8:9], v10, v[186:187]
	v_lshlrev_b64 v[12:13], v14, v[176:177]
	v_min_u32_e32 v8, 1, v8
	v_min_u32_e32 v12, 1, v12
	v_or_b32_e32 v8, v9, v8
	v_or_b32_e32 v12, v13, v12
	v_cvt_f32_u32_e32 v8, v8
	v_cvt_f32_u32_e32 v12, v12
	v_sub_u32_e32 v9, 32, v10
	v_sub_u32_e32 v13, 32, v14
	v_ldexp_f32 v8, v8, v9
	v_ldexp_f32 v12, v12, v13
	v_fma_f32 v8, v8, s80, v4
	v_fma_f32 v12, v12, s80, v4
	v_mul_f32_e32 v9, 0x4b800000, v8
	v_mul_f32_e32 v13, 0x4b800000, v12
	v_cmp_gt_f32_e32 vcc, s92, v8
	v_cmp_gt_f32_e64 s[12:13], s92, v12
	s_nop 0
	v_cndmask_b32_e32 v8, v8, v9, vcc
	v_cndmask_b32_e64 v12, v12, v13, s[12:13]
	v_rsq_f32_e32 v8, v8
	v_rsq_f32_e32 v12, v12
	v_mul_f32_e32 v9, 0x45800000, v8
	v_mul_f32_e32 v13, 0x45800000, v12
	v_cndmask_b32_e32 v8, v8, v9, vcc
	v_cndmask_b32_e64 v12, v12, v13, s[12:13]
	v_mul_f32_e32 v8, 0x3c800000, v8
	v_mul_f32_e32 v12, 0x3c800000, v12
	v_mul_f32_e32 v246, 0xbfb8aa3b, v8
	v_mul_f32_e32 v248, 0xbfb8aa3b, v12
	v_mul_f32_e32 v9, v8, v8
	v_mul_f32_e32 v13, v12, v12
	v_mul_f32_e32 v247, 0x41000000, v9
	v_mul_f32_e32 v249, 0x41000000, v13
	v_ffbh_u32_e32 v8, v189
	v_ffbh_u32_e32 v12, v175
	v_min_u32_e32 v10, 32, v8
	v_min_u32_e32 v14, 32, v12
	v_lshlrev_b64 v[8:9], v10, v[188:189]
	v_lshlrev_b64 v[12:13], v14, v[174:175]
	v_min_u32_e32 v8, 1, v8
	v_min_u32_e32 v12, 1, v12
	v_or_b32_e32 v8, v9, v8
	v_or_b32_e32 v12, v13, v12
	v_cvt_f32_u32_e32 v8, v8
	v_cvt_f32_u32_e32 v12, v12
	v_sub_u32_e32 v9, 32, v10
	v_sub_u32_e32 v13, 32, v14
	v_ldexp_f32 v8, v8, v9
	v_ldexp_f32 v12, v12, v13
	v_fma_f32 v8, v8, s80, v4
	v_fma_f32 v12, v12, s80, v4
	v_mul_f32_e32 v9, 0x4b800000, v8
	v_mul_f32_e32 v13, 0x4b800000, v12
	v_cmp_gt_f32_e32 vcc, s92, v8
	v_cmp_gt_f32_e64 s[12:13], s92, v12
	s_nop 0
	v_cndmask_b32_e32 v8, v8, v9, vcc
	v_cndmask_b32_e64 v12, v12, v13, s[12:13]
	v_rsq_f32_e32 v8, v8
	v_rsq_f32_e32 v12, v12
	v_mul_f32_e32 v9, 0x45800000, v8
	v_mul_f32_e32 v13, 0x45800000, v12
	v_cndmask_b32_e32 v8, v8, v9, vcc
	v_cndmask_b32_e64 v12, v12, v13, s[12:13]
	v_mul_f32_e32 v8, 0x3c800000, v8
	v_mul_f32_e32 v12, 0x3c800000, v12
	v_mul_f32_e32 v250, 0xbfb8aa3b, v8
	v_mul_f32_e32 v252, 0xbfb8aa3b, v12
	v_mul_f32_e32 v9, v8, v8
	v_mul_f32_e32 v13, v12, v12
	v_mul_f32_e32 v251, 0x41000000, v9
	v_mul_f32_e32 v253, 0x41000000, v13
	v_pk_mul_f32 v[222:223], v[156:157], v[194:195] op_sel_hi:[1,0]
	v_pk_mul_f32 v[224:225], v[158:159], v[194:195] op_sel_hi:[1,0]
	v_pk_mul_f32 v[226:227], v[152:153], v[194:195] op_sel_hi:[1,0]
	v_pk_mul_f32 v[228:229], v[154:155], v[194:195] op_sel_hi:[1,0]
	v_mad_i64_i32 v[16:17], vcc, v190, s93, v[2:3]
	v_exp_f32_e32 v222, v222
	v_exp_f32_e32 v223, v223
	v_exp_f32_e32 v224, v224
	v_exp_f32_e32 v225, v225
	v_exp_f32_e32 v226, v226
	v_exp_f32_e32 v227, v227
	v_exp_f32_e32 v228, v228
	v_exp_f32_e32 v229, v229
	v_pk_mul_f32 v[238:239], v[156:157], v[148:149]
	v_pk_mul_f32 v[240:241], v[158:159], v[150:151]
; __device__ __forceinline__ unsigned pk4_fp8(float a, float b, float c, float d) { int w = 0; w = __builtin_amdgcn_cvt_pk_fp8_f32(clamp8(a), clamp8(b), w, false); w = __builtin_amdgcn_cvt_pk_fp8_f32(clamp8(c), clamp8(d), w, true); return (unsigned)w; }
; __device__ __forceinline__ float silu_mul(float g, float u) { return g * __builtin_amdgcn_rcpf(1.0f + __builtin_amdgcn_exp2f(-g * LOG2E)) * u; }
;     __device__ __forceinline__ void operator()(const f32x4 (&acc)[2][2][4][2], const Unit& u, int wr, int wc, int fr, int fq, const unsigned long long (&pf)[8]) const {
;     ...
;             for (int m = 0; m < 4; ++m) { const int row = row0 + ai * HALF + m * 16; const float rs = rsqrtf((float)pf[ai * 4 + m] * (1.0f / (SSQ_SCALE * 1024.0f)) + EPS) * wsc;
;                 const f32x4 g0 = acc[ai][0][m][0] * rs, g1 = acc[ai][0][m][1] * rs, u0 = acc[ai][1][m][0] * rs, u1 = acc[ai][1][m][1] * rs;
;                 u32x2 w; w.x = pk4_fp8(silu_mul(g0[0], u0[0]) * HFF8_SCALE, silu_mul(g0[1], u0[1]) * HFF8_SCALE, silu_mul(g0[2], u0[2]) * HFF8_SCALE, silu_mul(g0[3], u0[3]) * HFF8_SCALE);
;                 w.y = pk4_fp8(silu_mul(g1[0], u1[0]) * HFF8_SCALE, silu_mul(g1[1], u1[1]) * HFF8_SCALE, silu_mul(g1[2], u1[2]) * HFF8_SCALE, silu_mul(g1[3], u1[3]) * HFF8_SCALE);
;                 *(u32x2*)(O + (size_t)row * FF + col0) = w; }
	v_pk_mul_f32 v[242:243], v[152:153], v[144:145]
	v_pk_mul_f32 v[244:245], v[154:155], v[146:147]
	v_pk_add_f32 v[230:231], v[222:223], v[6:7]
	v_pk_add_f32 v[232:233], v[224:225], v[6:7]
	v_pk_add_f32 v[234:235], v[226:227], v[6:7]
	v_pk_add_f32 v[236:237], v[228:229], v[6:7]
	v_lshl_add_u64 v[16:17], v[16:17], 0, v[0:1]
	v_rcp_f32_e32 v230, v230
	v_rcp_f32_e32 v231, v231
	v_rcp_f32_e32 v232, v232
	v_rcp_f32_e32 v233, v233
	v_rcp_f32_e32 v234, v234
	v_rcp_f32_e32 v235, v235
	v_rcp_f32_e32 v236, v236
	v_rcp_f32_e32 v237, v237
	v_pk_mul_f32 v[238:239], v[238:239], v[194:195] op_sel:[0,1] op_sel_hi:[1,1]
	v_pk_mul_f32 v[240:241], v[240:241], v[194:195] op_sel:[0,1] op_sel_hi:[1,1]
	v_pk_mul_f32 v[242:243], v[242:243], v[194:195] op_sel:[0,1] op_sel_hi:[1,1]
	v_pk_mul_f32 v[244:245], v[244:245], v[194:195] op_sel:[0,1] op_sel_hi:[1,1]
	v_pk_mul_f32 v[238:239], v[238:239], v[230:231]
	v_pk_mul_f32 v[240:241], v[240:241], v[232:233]
	v_pk_mul_f32 v[242:243], v[242:243], v[234:235]
	v_pk_mul_f32 v[244:245], v[244:245], v[236:237]
	v_med3_f32 v238, v238, s38, v210
	v_med3_f32 v239, v239, s38, v210
	v_med3_f32 v240, v240, s38, v210
	v_med3_f32 v241, v241, s38, v210
	v_med3_f32 v242, v242, s38, v210
	v_med3_f32 v243, v243, s38, v210
	v_med3_f32 v244, v244, s38, v210
	v_med3_f32 v245, v245, s38, v210
	v_cvt_pk_fp8_f32 v20, v238, v239
	v_cvt_pk_fp8_f32 v21, v242, v243
	v_cvt_pk_fp8_f32 v20, v240, v241 op_sel:[0,0,1]
	v_cvt_pk_fp8_f32 v21, v244, v245 op_sel:[0,0,1]
	s_nop 0
	global_store_dwordx2 v[16:17], v[20:21], off
	v_add_u32_e32 v24, 0x10, v190
	v_pk_mul_f32 v[222:223], v[140:141], v[196:197] op_sel_hi:[1,0]
	v_pk_mul_f32 v[224:225], v[142:143], v[196:197] op_sel_hi:[1,0]
	v_pk_mul_f32 v[226:227], v[136:137], v[196:197] op_sel_hi:[1,0]
	v_pk_mul_f32 v[228:229], v[138:139], v[196:197] op_sel_hi:[1,0]
	v_mad_i64_i32 v[18:19], vcc, v24, s93, v[2:3]
	v_exp_f32_e32 v222, v222
	v_exp_f32_e32 v223, v223
	v_exp_f32_e32 v224, v224
	v_exp_f32_e32 v225, v225
	v_exp_f32_e32 v226, v226
	v_exp_f32_e32 v227, v227
	v_exp_f32_e32 v228, v228
	v_exp_f32_e32 v229, v229
	v_pk_mul_f32 v[238:239], v[140:141], v[132:133]
	v_pk_mul_f32 v[240:241], v[142:143], v[134:135]
	v_pk_mul_f32 v[242:243], v[136:137], v[128:129]
	v_pk_mul_f32 v[244:245], v[138:139], v[130:131]
	v_pk_add_f32 v[230:231], v[222:223], v[6:7]
	v_pk_add_f32 v[232:233], v[224:225], v[6:7]
	v_pk_add_f32 v[234:235], v[226:227], v[6:7]
	v_pk_add_f32 v[236:237], v[228:229], v[6:7]
	v_lshl_add_u64 v[18:19], v[18:19], 0, v[0:1]
	v_rcp_f32_e32 v230, v230
	v_rcp_f32_e32 v231, v231
	v_rcp_f32_e32 v232, v232
	v_rcp_f32_e32 v233, v233
	v_rcp_f32_e32 v234, v234
	v_rcp_f32_e32 v235, v235
	v_rcp_f32_e32 v236, v236
	v_rcp_f32_e32 v237, v237
	v_pk_mul_f32 v[238:239], v[238:239], v[196:197] op_sel:[0,1] op_sel_hi:[1,1]
	v_pk_mul_f32 v[240:241], v[240:241], v[196:197] op_sel:[0,1] op_sel_hi:[1,1]
	v_pk_mul_f32 v[242:243], v[242:243], v[196:197] op_sel:[0,1] op_sel_hi:[1,1]
	v_pk_mul_f32 v[244:245], v[244:245], v[196:197] op_sel:[0,1] op_sel_hi:[1,1]
	v_pk_mul_f32 v[238:239], v[238:239], v[230:231]
	v_pk_mul_f32 v[240:241], v[240:241], v[232:233]
	v_pk_mul_f32 v[242:243], v[242:243], v[234:235]
	v_pk_mul_f32 v[244:245], v[244:245], v[236:237]
	v_med3_f32 v238, v238, s38, v210
	v_med3_f32 v239, v239, s38, v210
	v_med3_f32 v240, v240, s38, v210
	v_med3_f32 v241, v241, s38, v210
	v_med3_f32 v242, v242, s38, v210
	v_med3_f32 v243, v243, s38, v210
	v_med3_f32 v244, v244, s38, v210
	v_med3_f32 v245, v245, s38, v210
	v_cvt_pk_fp8_f32 v22, v238, v239
	v_cvt_pk_fp8_f32 v23, v242, v243
	v_cvt_pk_fp8_f32 v22, v240, v241 op_sel:[0,0,1]
	v_cvt_pk_fp8_f32 v23, v244, v245 op_sel:[0,0,1]
	s_nop 0
	global_store_dwordx2 v[18:19], v[22:23], off
	v_add_u32_e32 v24, 0x20, v190
	v_pk_mul_f32 v[222:223], v[124:125], v[198:199] op_sel_hi:[1,0]
	v_pk_mul_f32 v[224:225], v[126:127], v[198:199] op_sel_hi:[1,0]
	v_pk_mul_f32 v[226:227], v[120:121], v[198:199] op_sel_hi:[1,0]
	v_pk_mul_f32 v[228:229], v[122:123], v[198:199] op_sel_hi:[1,0]
	v_mad_i64_i32 v[16:17], vcc, v24, s93, v[2:3]
	v_exp_f32_e32 v222, v222
	v_exp_f32_e32 v223, v223
	v_exp_f32_e32 v224, v224
	v_exp_f32_e32 v225, v225
	v_exp_f32_e32 v226, v226
	v_exp_f32_e32 v227, v227
	v_exp_f32_e32 v228, v228
	v_exp_f32_e32 v229, v229
	v_pk_mul_f32 v[238:239], v[124:125], v[116:117]
	v_pk_mul_f32 v[240:241], v[126:127], v[118:119]
	v_pk_mul_f32 v[242:243], v[120:121], v[112:113]
	v_pk_mul_f32 v[244:245], v[122:123], v[114:115]
	v_pk_add_f32 v[230:231], v[222:223], v[6:7]
	v_pk_add_f32 v[232:233], v[224:225], v[6:7]
	v_pk_add_f32 v[234:235], v[226:227], v[6:7]
	v_pk_add_f32 v[236:237], v[228:229], v[6:7]
	v_lshl_add_u64 v[16:17], v[16:17], 0, v[0:1]
	v_rcp_f32_e32 v230, v230
	v_rcp_f32_e32 v231, v231
	v_rcp_f32_e32 v232, v232
	v_rcp_f32_e32 v233, v233
	v_rcp_f32_e32 v234, v234
	v_rcp_f32_e32 v235, v235
	v_rcp_f32_e32 v236, v236
	v_rcp_f32_e32 v237, v237
	v_pk_mul_f32 v[238:239], v[238:239], v[198:199] op_sel:[0,1] op_sel_hi:[1,1]
	v_pk_mul_f32 v[240:241], v[240:241], v[198:199] op_sel:[0,1] op_sel_hi:[1,1]
	v_pk_mul_f32 v[242:243], v[242:243], v[198:199] op_sel:[0,1] op_sel_hi:[1,1]
	v_pk_mul_f32 v[244:245], v[244:245], v[198:199] op_sel:[0,1] op_sel_hi:[1,1]
	v_pk_mul_f32 v[238:239], v[238:239], v[230:231]
	v_pk_mul_f32 v[240:241], v[240:241], v[232:233]
	v_pk_mul_f32 v[242:243], v[242:243], v[234:235]
	v_pk_mul_f32 v[244:245], v[244:245], v[236:237]
	v_med3_f32 v238, v238, s38, v210
	v_med3_f32 v239, v239, s38, v210
	v_med3_f32 v240, v240, s38, v210
	v_med3_f32 v241, v241, s38, v210
	v_med3_f32 v242, v242, s38, v210
	v_med3_f32 v243, v243, s38, v210
	v_med3_f32 v244, v244, s38, v210
; __device__ __forceinline__ unsigned pk4_fp8(float a, float b, float c, float d) { int w = 0; w = __builtin_amdgcn_cvt_pk_fp8_f32(clamp8(a), clamp8(b), w, false); w = __builtin_amdgcn_cvt_pk_fp8_f32(clamp8(c), clamp8(d), w, true); return (unsigned)w; }
; __device__ __forceinline__ float silu_mul(float g, float u) { return g * __builtin_amdgcn_rcpf(1.0f + __builtin_amdgcn_exp2f(-g * LOG2E)) * u; }
;     __device__ __forceinline__ void operator()(const f32x4 (&acc)[2][2][4][2], const Unit& u, int wr, int wc, int fr, int fq, const unsigned long long (&pf)[8]) const {
;     ...
;             for (int m = 0; m < 4; ++m) { const int row = row0 + ai * HALF + m * 16; const float rs = rsqrtf((float)pf[ai * 4 + m] * (1.0f / (SSQ_SCALE * 1024.0f)) + EPS) * wsc;
;                 const f32x4 g0 = acc[ai][0][m][0] * rs, g1 = acc[ai][0][m][1] * rs, u0 = acc[ai][1][m][0] * rs, u1 = acc[ai][1][m][1] * rs;
;                 u32x2 w; w.x = pk4_fp8(silu_mul(g0[0], u0[0]) * HFF8_SCALE, silu_mul(g0[1], u0[1]) * HFF8_SCALE, silu_mul(g0[2], u0[2]) * HFF8_SCALE, silu_mul(g0[3], u0[3]) * HFF8_SCALE);
;                 w.y = pk4_fp8(silu_mul(g1[0], u1[0]) * HFF8_SCALE, silu_mul(g1[1], u1[1]) * HFF8_SCALE, silu_mul(g1[2], u1[2]) * HFF8_SCALE, silu_mul(g1[3], u1[3]) * HFF8_SCALE);
;                 *(u32x2*)(O + (size_t)row * FF + col0) = w; }
	v_med3_f32 v245, v245, s38, v210
	v_cvt_pk_fp8_f32 v20, v238, v239
	v_cvt_pk_fp8_f32 v21, v242, v243
	v_cvt_pk_fp8_f32 v20, v240, v241 op_sel:[0,0,1]
	v_cvt_pk_fp8_f32 v21, v244, v245 op_sel:[0,0,1]
	s_nop 0
	global_store_dwordx2 v[16:17], v[20:21], off
	v_add_u32_e32 v24, 0x30, v190
	v_pk_mul_f32 v[222:223], v[108:109], v[200:201] op_sel_hi:[1,0]
	v_pk_mul_f32 v[224:225], v[110:111], v[200:201] op_sel_hi:[1,0]
	v_pk_mul_f32 v[226:227], v[104:105], v[200:201] op_sel_hi:[1,0]
	v_pk_mul_f32 v[228:229], v[106:107], v[200:201] op_sel_hi:[1,0]
	v_mad_i64_i32 v[18:19], vcc, v24, s93, v[2:3]
	v_exp_f32_e32 v222, v222
	v_exp_f32_e32 v223, v223
	v_exp_f32_e32 v224, v224
	v_exp_f32_e32 v225, v225
	v_exp_f32_e32 v226, v226
	v_exp_f32_e32 v227, v227
	v_exp_f32_e32 v228, v228
	v_exp_f32_e32 v229, v229
	v_pk_mul_f32 v[238:239], v[108:109], v[100:101]
	v_pk_mul_f32 v[240:241], v[110:111], v[102:103]
	v_pk_mul_f32 v[242:243], v[104:105], v[96:97]
	v_pk_mul_f32 v[244:245], v[106:107], v[98:99]
	v_pk_add_f32 v[230:231], v[222:223], v[6:7]
	v_pk_add_f32 v[232:233], v[224:225], v[6:7]
	v_pk_add_f32 v[234:235], v[226:227], v[6:7]
	v_pk_add_f32 v[236:237], v[228:229], v[6:7]
	v_lshl_add_u64 v[18:19], v[18:19], 0, v[0:1]
	v_rcp_f32_e32 v230, v230
	v_rcp_f32_e32 v231, v231
	v_rcp_f32_e32 v232, v232
	v_rcp_f32_e32 v233, v233
	v_rcp_f32_e32 v234, v234
	v_rcp_f32_e32 v235, v235
	v_rcp_f32_e32 v236, v236
	v_rcp_f32_e32 v237, v237
	v_pk_mul_f32 v[238:239], v[238:239], v[200:201] op_sel:[0,1] op_sel_hi:[1,1]
	v_pk_mul_f32 v[240:241], v[240:241], v[200:201] op_sel:[0,1] op_sel_hi:[1,1]
	v_pk_mul_f32 v[242:243], v[242:243], v[200:201] op_sel:[0,1] op_sel_hi:[1,1]
	v_pk_mul_f32 v[244:245], v[244:245], v[200:201] op_sel:[0,1] op_sel_hi:[1,1]
	v_pk_mul_f32 v[238:239], v[238:239], v[230:231]
	v_pk_mul_f32 v[240:241], v[240:241], v[232:233]
	v_pk_mul_f32 v[242:243], v[242:243], v[234:235]
	v_pk_mul_f32 v[244:245], v[244:245], v[236:237]
	v_med3_f32 v238, v238, s38, v210
	v_med3_f32 v239, v239, s38, v210
	v_med3_f32 v240, v240, s38, v210
	v_med3_f32 v241, v241, s38, v210
	v_med3_f32 v242, v242, s38, v210
	v_med3_f32 v243, v243, s38, v210
	v_med3_f32 v244, v244, s38, v210
	v_med3_f32 v245, v245, s38, v210
	v_cvt_pk_fp8_f32 v22, v238, v239
	v_cvt_pk_fp8_f32 v23, v242, v243
	v_cvt_pk_fp8_f32 v22, v240, v241 op_sel:[0,0,1]
	v_cvt_pk_fp8_f32 v23, v244, v245 op_sel:[0,0,1]
	s_nop 0
	global_store_dwordx2 v[18:19], v[22:23], off
	v_add_u32_e32 v24, 0x80, v190
	v_pk_mul_f32 v[222:223], v[92:93], v[246:247] op_sel_hi:[1,0]
	v_pk_mul_f32 v[224:225], v[94:95], v[246:247] op_sel_hi:[1,0]
	v_pk_mul_f32 v[226:227], v[88:89], v[246:247] op_sel_hi:[1,0]
	v_pk_mul_f32 v[228:229], v[90:91], v[246:247] op_sel_hi:[1,0]
	v_mad_i64_i32 v[16:17], vcc, v24, s93, v[2:3]
	v_exp_f32_e32 v222, v222
	v_exp_f32_e32 v223, v223
	v_exp_f32_e32 v224, v224
	v_exp_f32_e32 v225, v225
	v_exp_f32_e32 v226, v226
	v_exp_f32_e32 v227, v227
	v_exp_f32_e32 v228, v228
	v_exp_f32_e32 v229, v229
	v_pk_mul_f32 v[238:239], v[92:93], v[84:85]
	v_pk_mul_f32 v[240:241], v[94:95], v[86:87]
	v_pk_mul_f32 v[242:243], v[88:89], v[80:81]
	v_pk_mul_f32 v[244:245], v[90:91], v[82:83]
	v_pk_add_f32 v[230:231], v[222:223], v[6:7]
	v_pk_add_f32 v[232:233], v[224:225], v[6:7]
	v_pk_add_f32 v[234:235], v[226:227], v[6:7]
	v_pk_add_f32 v[236:237], v[228:229], v[6:7]
	v_lshl_add_u64 v[16:17], v[16:17], 0, v[0:1]
	v_rcp_f32_e32 v230, v230
	v_rcp_f32_e32 v231, v231
	v_rcp_f32_e32 v232, v232
	v_rcp_f32_e32 v233, v233
	v_rcp_f32_e32 v234, v234
	v_rcp_f32_e32 v235, v235
	v_rcp_f32_e32 v236, v236
	v_rcp_f32_e32 v237, v237
	v_pk_mul_f32 v[238:239], v[238:239], v[246:247] op_sel:[0,1] op_sel_hi:[1,1]
	v_pk_mul_f32 v[240:241], v[240:241], v[246:247] op_sel:[0,1] op_sel_hi:[1,1]
	v_pk_mul_f32 v[242:243], v[242:243], v[246:247] op_sel:[0,1] op_sel_hi:[1,1]
	v_pk_mul_f32 v[244:245], v[244:245], v[246:247] op_sel:[0,1] op_sel_hi:[1,1]
	v_pk_mul_f32 v[238:239], v[238:239], v[230:231]
	v_pk_mul_f32 v[240:241], v[240:241], v[232:233]
	v_pk_mul_f32 v[242:243], v[242:243], v[234:235]
	v_pk_mul_f32 v[244:245], v[244:245], v[236:237]
	v_med3_f32 v238, v238, s38, v210
	v_med3_f32 v239, v239, s38, v210
	v_med3_f32 v240, v240, s38, v210
	v_med3_f32 v241, v241, s38, v210
	v_med3_f32 v242, v242, s38, v210
	v_med3_f32 v243, v243, s38, v210
	v_med3_f32 v244, v244, s38, v210
	v_med3_f32 v245, v245, s38, v210
	v_cvt_pk_fp8_f32 v20, v238, v239
	v_cvt_pk_fp8_f32 v21, v242, v243
	v_cvt_pk_fp8_f32 v20, v240, v241 op_sel:[0,0,1]
	v_cvt_pk_fp8_f32 v21, v244, v245 op_sel:[0,0,1]
	s_nop 0
	global_store_dwordx2 v[16:17], v[20:21], off
	v_add_u32_e32 v24, 0x90, v190
	v_pk_mul_f32 v[222:223], v[76:77], v[248:249] op_sel_hi:[1,0]
	v_pk_mul_f32 v[224:225], v[78:79], v[248:249] op_sel_hi:[1,0]
	v_pk_mul_f32 v[226:227], v[72:73], v[248:249] op_sel_hi:[1,0]
	v_pk_mul_f32 v[228:229], v[74:75], v[248:249] op_sel_hi:[1,0]
	v_mad_i64_i32 v[18:19], vcc, v24, s93, v[2:3]
	v_exp_f32_e32 v222, v222
	v_exp_f32_e32 v223, v223
	v_exp_f32_e32 v224, v224
	v_exp_f32_e32 v225, v225
	v_exp_f32_e32 v226, v226
	v_exp_f32_e32 v227, v227
	v_exp_f32_e32 v228, v228
	v_exp_f32_e32 v229, v229
	v_pk_mul_f32 v[238:239], v[76:77], v[68:69]
	v_pk_mul_f32 v[240:241], v[78:79], v[70:71]
	v_pk_mul_f32 v[242:243], v[72:73], v[64:65]
	v_pk_mul_f32 v[244:245], v[74:75], v[66:67]
	v_pk_add_f32 v[230:231], v[222:223], v[6:7]
	v_pk_add_f32 v[232:233], v[224:225], v[6:7]
	v_pk_add_f32 v[234:235], v[226:227], v[6:7]
	v_pk_add_f32 v[236:237], v[228:229], v[6:7]
	v_lshl_add_u64 v[18:19], v[18:19], 0, v[0:1]
	v_rcp_f32_e32 v230, v230
	v_rcp_f32_e32 v231, v231
	v_rcp_f32_e32 v232, v232
; __device__ __forceinline__ unsigned pk4_fp8(float a, float b, float c, float d) { int w = 0; w = __builtin_amdgcn_cvt_pk_fp8_f32(clamp8(a), clamp8(b), w, false); w = __builtin_amdgcn_cvt_pk_fp8_f32(clamp8(c), clamp8(d), w, true); return (unsigned)w; }
; __device__ __forceinline__ float silu_mul(float g, float u) { return g * __builtin_amdgcn_rcpf(1.0f + __builtin_amdgcn_exp2f(-g * LOG2E)) * u; }
;     __device__ __forceinline__ void operator()(const f32x4 (&acc)[2][2][4][2], const Unit& u, int wr, int wc, int fr, int fq, const unsigned long long (&pf)[8]) const {
;     ...
;             for (int m = 0; m < 4; ++m) { const int row = row0 + ai * HALF + m * 16; const float rs = rsqrtf((float)pf[ai * 4 + m] * (1.0f / (SSQ_SCALE * 1024.0f)) + EPS) * wsc;
;                 const f32x4 g0 = acc[ai][0][m][0] * rs, g1 = acc[ai][0][m][1] * rs, u0 = acc[ai][1][m][0] * rs, u1 = acc[ai][1][m][1] * rs;
;                 u32x2 w; w.x = pk4_fp8(silu_mul(g0[0], u0[0]) * HFF8_SCALE, silu_mul(g0[1], u0[1]) * HFF8_SCALE, silu_mul(g0[2], u0[2]) * HFF8_SCALE, silu_mul(g0[3], u0[3]) * HFF8_SCALE);
;                 w.y = pk4_fp8(silu_mul(g1[0], u1[0]) * HFF8_SCALE, silu_mul(g1[1], u1[1]) * HFF8_SCALE, silu_mul(g1[2], u1[2]) * HFF8_SCALE, silu_mul(g1[3], u1[3]) * HFF8_SCALE);
;                 *(u32x2*)(O + (size_t)row * FF + col0) = w; }
	v_rcp_f32_e32 v233, v233
	v_rcp_f32_e32 v234, v234
	v_rcp_f32_e32 v235, v235
	v_rcp_f32_e32 v236, v236
	v_rcp_f32_e32 v237, v237
	v_pk_mul_f32 v[238:239], v[238:239], v[248:249] op_sel:[0,1] op_sel_hi:[1,1]
	v_pk_mul_f32 v[240:241], v[240:241], v[248:249] op_sel:[0,1] op_sel_hi:[1,1]
	v_pk_mul_f32 v[242:243], v[242:243], v[248:249] op_sel:[0,1] op_sel_hi:[1,1]
	v_pk_mul_f32 v[244:245], v[244:245], v[248:249] op_sel:[0,1] op_sel_hi:[1,1]
	v_pk_mul_f32 v[238:239], v[238:239], v[230:231]
	v_pk_mul_f32 v[240:241], v[240:241], v[232:233]
	v_pk_mul_f32 v[242:243], v[242:243], v[234:235]
	v_pk_mul_f32 v[244:245], v[244:245], v[236:237]
	v_med3_f32 v238, v238, s38, v210
	v_med3_f32 v239, v239, s38, v210
	v_med3_f32 v240, v240, s38, v210
	v_med3_f32 v241, v241, s38, v210
	v_med3_f32 v242, v242, s38, v210
	v_med3_f32 v243, v243, s38, v210
	v_med3_f32 v244, v244, s38, v210
	v_med3_f32 v245, v245, s38, v210
	v_cvt_pk_fp8_f32 v22, v238, v239
	v_cvt_pk_fp8_f32 v23, v242, v243
	v_cvt_pk_fp8_f32 v22, v240, v241 op_sel:[0,0,1]
	v_cvt_pk_fp8_f32 v23, v244, v245 op_sel:[0,0,1]
	s_nop 0
	global_store_dwordx2 v[18:19], v[22:23], off
	v_add_u32_e32 v24, 0xa0, v190
	v_pk_mul_f32 v[222:223], v[60:61], v[250:251] op_sel_hi:[1,0]
	v_pk_mul_f32 v[224:225], v[62:63], v[250:251] op_sel_hi:[1,0]
	v_pk_mul_f32 v[226:227], v[56:57], v[250:251] op_sel_hi:[1,0]
	v_pk_mul_f32 v[228:229], v[58:59], v[250:251] op_sel_hi:[1,0]
	v_mad_i64_i32 v[16:17], vcc, v24, s93, v[2:3]
	v_exp_f32_e32 v222, v222
	v_exp_f32_e32 v223, v223
	v_exp_f32_e32 v224, v224
	v_exp_f32_e32 v225, v225
	v_exp_f32_e32 v226, v226
	v_exp_f32_e32 v227, v227
	v_exp_f32_e32 v228, v228
	v_exp_f32_e32 v229, v229
	v_pk_mul_f32 v[238:239], v[60:61], v[52:53]
	v_pk_mul_f32 v[240:241], v[62:63], v[54:55]
	v_pk_mul_f32 v[242:243], v[56:57], v[48:49]
	v_pk_mul_f32 v[244:245], v[58:59], v[50:51]
	v_pk_add_f32 v[230:231], v[222:223], v[6:7]
	v_pk_add_f32 v[232:233], v[224:225], v[6:7]
	v_pk_add_f32 v[234:235], v[226:227], v[6:7]
	v_pk_add_f32 v[236:237], v[228:229], v[6:7]
	v_lshl_add_u64 v[16:17], v[16:17], 0, v[0:1]
	v_rcp_f32_e32 v230, v230
	v_rcp_f32_e32 v231, v231
	v_rcp_f32_e32 v232, v232
	v_rcp_f32_e32 v233, v233
	v_rcp_f32_e32 v234, v234
	v_rcp_f32_e32 v235, v235
	v_rcp_f32_e32 v236, v236
	v_rcp_f32_e32 v237, v237
	v_pk_mul_f32 v[238:239], v[238:239], v[250:251] op_sel:[0,1] op_sel_hi:[1,1]
	v_pk_mul_f32 v[240:241], v[240:241], v[250:251] op_sel:[0,1] op_sel_hi:[1,1]
	v_pk_mul_f32 v[242:243], v[242:243], v[250:251] op_sel:[0,1] op_sel_hi:[1,1]
	v_pk_mul_f32 v[244:245], v[244:245], v[250:251] op_sel:[0,1] op_sel_hi:[1,1]
	v_pk_mul_f32 v[238:239], v[238:239], v[230:231]
	v_pk_mul_f32 v[240:241], v[240:241], v[232:233]
	v_pk_mul_f32 v[242:243], v[242:243], v[234:235]
	v_pk_mul_f32 v[244:245], v[244:245], v[236:237]
	v_med3_f32 v238, v238, s38, v210
	v_med3_f32 v239, v239, s38, v210
	v_med3_f32 v240, v240, s38, v210
	v_med3_f32 v241, v241, s38, v210
	v_med3_f32 v242, v242, s38, v210
	v_med3_f32 v243, v243, s38, v210
	v_med3_f32 v244, v244, s38, v210
	v_med3_f32 v245, v245, s38, v210
	v_cvt_pk_fp8_f32 v20, v238, v239
	v_cvt_pk_fp8_f32 v21, v242, v243
	v_cvt_pk_fp8_f32 v20, v240, v241 op_sel:[0,0,1]
	v_cvt_pk_fp8_f32 v21, v244, v245 op_sel:[0,0,1]
	s_nop 0
	global_store_dwordx2 v[16:17], v[20:21], off
	v_add_u32_e32 v24, 0xb0, v190
	v_pk_mul_f32 v[222:223], v[44:45], v[252:253] op_sel_hi:[1,0]
	v_pk_mul_f32 v[224:225], v[46:47], v[252:253] op_sel_hi:[1,0]
	v_pk_mul_f32 v[226:227], v[40:41], v[252:253] op_sel_hi:[1,0]
	v_pk_mul_f32 v[228:229], v[42:43], v[252:253] op_sel_hi:[1,0]
	v_mad_i64_i32 v[18:19], vcc, v24, s93, v[2:3]
	v_exp_f32_e32 v222, v222
	v_exp_f32_e32 v223, v223
	v_exp_f32_e32 v224, v224
	v_exp_f32_e32 v225, v225
	v_exp_f32_e32 v226, v226
	v_exp_f32_e32 v227, v227
	v_exp_f32_e32 v228, v228
	v_exp_f32_e32 v229, v229
	v_pk_mul_f32 v[238:239], v[44:45], v[36:37]
	v_pk_mul_f32 v[240:241], v[46:47], v[38:39]
	v_pk_mul_f32 v[242:243], v[40:41], v[32:33]
	v_pk_mul_f32 v[244:245], v[42:43], v[34:35]
	v_pk_add_f32 v[230:231], v[222:223], v[6:7]
	v_pk_add_f32 v[232:233], v[224:225], v[6:7]
	v_pk_add_f32 v[234:235], v[226:227], v[6:7]
	v_pk_add_f32 v[236:237], v[228:229], v[6:7]
	v_lshl_add_u64 v[18:19], v[18:19], 0, v[0:1]
	v_rcp_f32_e32 v230, v230
	v_rcp_f32_e32 v231, v231
	v_rcp_f32_e32 v232, v232
	v_rcp_f32_e32 v233, v233
	v_rcp_f32_e32 v234, v234
	v_rcp_f32_e32 v235, v235
	v_rcp_f32_e32 v236, v236
	v_rcp_f32_e32 v237, v237
	v_pk_mul_f32 v[238:239], v[238:239], v[252:253] op_sel:[0,1] op_sel_hi:[1,1]
	v_pk_mul_f32 v[240:241], v[240:241], v[252:253] op_sel:[0,1] op_sel_hi:[1,1]
	v_pk_mul_f32 v[242:243], v[242:243], v[252:253] op_sel:[0,1] op_sel_hi:[1,1]
	v_pk_mul_f32 v[244:245], v[244:245], v[252:253] op_sel:[0,1] op_sel_hi:[1,1]
	v_pk_mul_f32 v[238:239], v[238:239], v[230:231]
	v_pk_mul_f32 v[240:241], v[240:241], v[232:233]
	v_pk_mul_f32 v[242:243], v[242:243], v[234:235]
	v_pk_mul_f32 v[244:245], v[244:245], v[236:237]
	v_med3_f32 v238, v238, s38, v210
	v_med3_f32 v239, v239, s38, v210
	v_med3_f32 v240, v240, s38, v210
	v_med3_f32 v241, v241, s38, v210
	v_med3_f32 v242, v242, s38, v210
	v_med3_f32 v243, v243, s38, v210
	v_med3_f32 v244, v244, s38, v210
	v_med3_f32 v245, v245, s38, v210
	v_cvt_pk_fp8_f32 v22, v238, v239
	v_cvt_pk_fp8_f32 v23, v242, v243
	v_cvt_pk_fp8_f32 v22, v240, v241 op_sel:[0,0,1]
	v_cvt_pk_fp8_f32 v23, v244, v245 op_sel:[0,0,1]
	s_nop 0
	global_store_dwordx2 v[18:19], v[22:23], off
	s_mov_b64 s[12:13], -1
	s_andn2_b64 vcc, exec, s[10:11]
	s_cbranch_vccnz .LBB0_237
	s_andn2_b64 vcc, exec, s[14:15]
	s_cbranch_vccnz .LBB0_236
	s_barrier
	s_branch .LBB0_236
